# v058 SEQ phase: static s_setprio 1 for waves 0,1,6,7 (each SIMD's critical-path wave)
# baseline (speedup 1.0000x reference)
;     const Frame F = refresh(F0);
;     const int odd = l & 1; const int nlin = B_ * (odd ? 4 : 8) * 2 * 4; const int ns5 = odd ? B_ * 2 * 32 : 0;
;     const int vcu = (F.G % 8 == 0) ? (F.bid % 8) * (F.G / 8) + F.bid / 8 : F.bid;
;     if (!odd || F.G <= nlin) {
;         for (int it = vcu; it < nlin + ns5; it += F.G) {
;             if (it < nlin) { if (mode != 2) seq_linear_item(F, l, it, mode >= 10 ? mode - 10 : 0); } else if (mode != 1 && mode < 10) seq_s5_item(F, l, it - nlin, 1);
.Lbw4_skip:
	s_waitcnt lgkmcnt(0)
	v_readlane_b32 s100, v251, 29
	s_add_i32 s100, s100, 2
	s_and_b32 s100, s100, 7
	s_cmp_ge_u32 s100, 4
	s_cbranch_scc1 .Lseq_prio_lo
	s_setprio 1
